# final RMSNorm pass rewritten by hand: 16 x 16-byte elements in flight per thread, gain vector hoisted, counted vmcnt so stores overlap remaining loads
# baseline (speedup 1.0000x reference)
; __device__ __forceinline__ void ph_final_norm(float* H, const float* __restrict__ rowss, const float* __restrict__ g, size_t gt, size_t NGT) {
;     const size_t n4 = (size_t)SEQ * DM / 4;
;     f32x4* h4 = (f32x4*)H;
;     for (size_t i0 = gt; i0 < n4; i0 += 8 * NGT) {
;         f32x4 v[8]; float rs[8];
; #pragma unroll
;         for (int k = 0; k < 8; ++k) { const size_t i = i0 + k * NGT; v[k] = h4[i]; rs[k] = rowss[i >> 10]; }
; #pragma unroll
;         for (int k = 0; k < 8; ++k) { const size_t i = i0 + k * NGT; const f32x4 gg = ((const f32x4*)g)[i & 1023]; h4[i] = v[k] * rsqrtf(rs[k] * (1.f / DM) + EPS) * gg; }
;     }
; }
; __global__ void __launch_bounds__(512, 2) k_fwd(Args a_unused) {
;     ...
;     if (IN(9)) { PH_IDS(); ph_final_norm(ap->out, ctl + CW_RSS3, ap->in[21], gt, NGT); }
.LBB0_1534:
	s_cmp_lt_i32 s76, 10
	s_cselect_b64 s[0:1], -1, 0
	s_and_b64 s[0:1], s[0:1], s[6:7]
	s_andn2_b64 vcc, exec, s[0:1]
	s_cbranch_vccnz .LBB0_1538
	s_cmpk_lg_i32 s74, 0x100
	s_cbranch_scc1 .Lp9_orig
	s_load_dwordx2 s[0:1], s[92:93], 0xb8
	s_load_dwordx4 s[16:19], s[92:93], 0xa8
	v_lshl_add_u32 v1, s2, 9, v0
	v_and_b32_e32 v2, 0x3ff, v1
	v_lshrrev_b32_e32 v3, 10, v1
	v_lshlrev_b32_e32 v2, 4, v2
	v_lshlrev_b32_e32 v4, 2, v3
	v_lshlrev_b32_e32 v1, 4, v1
	v_add_u32_e32 v5, 0x1000, v4
	v_mov_b32_e32 v10, 0x358637bd
	s_waitcnt lgkmcnt(0)
	s_add_u32 s20, s0, 0x60000
	s_addc_u32 s21, s1, 0
	global_load_dwordx4 v[6:9], v2, s[16:17]
	s_mov_b32 s22, 0
	s_mov_b64 s[24:25], s[18:19]
.Lp9_loop:
	global_load_dword v12, v4, s[20:21] offset:0
	global_load_dword v14, v4, s[20:21] offset:512
	global_load_dword v16, v4, s[20:21] offset:1024
	global_load_dword v18, v4, s[20:21] offset:1536
	global_load_dword v20, v4, s[20:21] offset:2048
	global_load_dword v22, v4, s[20:21] offset:2560
	global_load_dword v24, v4, s[20:21] offset:3072
	global_load_dword v26, v4, s[20:21] offset:3584
	global_load_dword v28, v5, s[20:21] offset:0
	global_load_dword v30, v5, s[20:21] offset:512
	global_load_dword v32, v5, s[20:21] offset:1024
	global_load_dword v34, v5, s[20:21] offset:1536
	global_load_dword v36, v5, s[20:21] offset:2048
	global_load_dword v38, v5, s[20:21] offset:2560
	global_load_dword v40, v5, s[20:21] offset:3072
	global_load_dword v42, v5, s[20:21] offset:3584
	s_mov_b64 s[26:27], s[24:25]
	global_load_dwordx4 v[44:47], v1, s[26:27]
	s_add_u32 s26, s26, 0x200000
	s_addc_u32 s27, s27, 0
	global_load_dwordx4 v[48:51], v1, s[26:27]
	s_add_u32 s26, s26, 0x200000
	s_addc_u32 s27, s27, 0
	global_load_dwordx4 v[52:55], v1, s[26:27]
	s_add_u32 s26, s26, 0x200000
	s_addc_u32 s27, s27, 0
	global_load_dwordx4 v[56:59], v1, s[26:27]
	s_add_u32 s26, s26, 0x200000
	s_addc_u32 s27, s27, 0
	global_load_dwordx4 v[60:63], v1, s[26:27]
	s_add_u32 s26, s26, 0x200000
	s_addc_u32 s27, s27, 0
	global_load_dwordx4 v[64:67], v1, s[26:27]
	s_add_u32 s26, s26, 0x200000
	s_addc_u32 s27, s27, 0
	global_load_dwordx4 v[68:71], v1, s[26:27]
	s_add_u32 s26, s26, 0x200000
	s_addc_u32 s27, s27, 0
	global_load_dwordx4 v[72:75], v1, s[26:27]
	s_add_u32 s26, s26, 0x200000
	s_addc_u32 s27, s27, 0
	global_load_dwordx4 v[76:79], v1, s[26:27]
	s_add_u32 s26, s26, 0x200000
	s_addc_u32 s27, s27, 0
	global_load_dwordx4 v[80:83], v1, s[26:27]
	s_add_u32 s26, s26, 0x200000
	s_addc_u32 s27, s27, 0
	global_load_dwordx4 v[84:87], v1, s[26:27]
	s_add_u32 s26, s26, 0x200000
	s_addc_u32 s27, s27, 0
	global_load_dwordx4 v[88:91], v1, s[26:27]
	s_add_u32 s26, s26, 0x200000
	s_addc_u32 s27, s27, 0
	global_load_dwordx4 v[92:95], v1, s[26:27]
	s_add_u32 s26, s26, 0x200000
	s_addc_u32 s27, s27, 0
	global_load_dwordx4 v[96:99], v1, s[26:27]
	s_add_u32 s26, s26, 0x200000
	s_addc_u32 s27, s27, 0
	global_load_dwordx4 v[100:103], v1, s[26:27]
	s_add_u32 s26, s26, 0x200000
	s_addc_u32 s27, s27, 0
	global_load_dwordx4 v[104:107], v1, s[26:27]
	s_mov_b64 s[26:27], s[24:25]
	s_waitcnt vmcnt(16)
	v_fmamk_f32 v12, v12, 0x39800000, v10
	v_fmamk_f32 v14, v14, 0x39800000, v10
	v_fmamk_f32 v16, v16, 0x39800000, v10
	v_fmamk_f32 v18, v18, 0x39800000, v10
	v_fmamk_f32 v20, v20, 0x39800000, v10
	v_fmamk_f32 v22, v22, 0x39800000, v10
	v_fmamk_f32 v24, v24, 0x39800000, v10
	v_fmamk_f32 v26, v26, 0x39800000, v10
	v_fmamk_f32 v28, v28, 0x39800000, v10
	v_fmamk_f32 v30, v30, 0x39800000, v10
	v_fmamk_f32 v32, v32, 0x39800000, v10
	v_fmamk_f32 v34, v34, 0x39800000, v10
	v_fmamk_f32 v36, v36, 0x39800000, v10
	v_fmamk_f32 v38, v38, 0x39800000, v10
	v_fmamk_f32 v40, v40, 0x39800000, v10
	v_fmamk_f32 v42, v42, 0x39800000, v10
	v_rsq_f32_e32 v12, v12
	v_rsq_f32_e32 v14, v14
	v_rsq_f32_e32 v16, v16
	v_rsq_f32_e32 v18, v18
	v_rsq_f32_e32 v20, v20
	v_rsq_f32_e32 v22, v22
	v_rsq_f32_e32 v24, v24
	v_rsq_f32_e32 v26, v26
	v_rsq_f32_e32 v28, v28
	v_rsq_f32_e32 v30, v30
	v_rsq_f32_e32 v32, v32
	v_rsq_f32_e32 v34, v34
	v_rsq_f32_e32 v36, v36
	v_rsq_f32_e32 v38, v38
	v_rsq_f32_e32 v40, v40
	v_rsq_f32_e32 v42, v42
	s_nop 0
	s_waitcnt vmcnt(15)
	v_pk_mul_f32 v[44:45], v[44:45], v[12:13] op_sel_hi:[1,0]
	v_pk_mul_f32 v[46:47], v[46:47], v[12:13] op_sel_hi:[1,0]
	v_pk_mul_f32 v[44:45], v[44:45], v[6:7]
	v_pk_mul_f32 v[46:47], v[46:47], v[8:9]
	global_store_dwordx4 v1, v[44:47], s[26:27]
	s_add_u32 s26, s26, 0x200000
	s_addc_u32 s27, s27, 0
	s_waitcnt vmcnt(15)
	v_pk_mul_f32 v[48:49], v[48:49], v[14:15] op_sel_hi:[1,0]
	v_pk_mul_f32 v[50:51], v[50:51], v[14:15] op_sel_hi:[1,0]
	v_pk_mul_f32 v[48:49], v[48:49], v[6:7]
	v_pk_mul_f32 v[50:51], v[50:51], v[8:9]
	global_store_dwordx4 v1, v[48:51], s[26:27]
	s_add_u32 s26, s26, 0x200000
	s_addc_u32 s27, s27, 0
	s_waitcnt vmcnt(15)
	v_pk_mul_f32 v[52:53], v[52:53], v[16:17] op_sel_hi:[1,0]
	v_pk_mul_f32 v[54:55], v[54:55], v[16:17] op_sel_hi:[1,0]
	v_pk_mul_f32 v[52:53], v[52:53], v[6:7]
	v_pk_mul_f32 v[54:55], v[54:55], v[8:9]
	global_store_dwordx4 v1, v[52:55], s[26:27]
	s_add_u32 s26, s26, 0x200000
	s_addc_u32 s27, s27, 0
	s_waitcnt vmcnt(15)
	v_pk_mul_f32 v[56:57], v[56:57], v[18:19] op_sel_hi:[1,0]
	v_pk_mul_f32 v[58:59], v[58:59], v[18:19] op_sel_hi:[1,0]
	v_pk_mul_f32 v[56:57], v[56:57], v[6:7]
	v_pk_mul_f32 v[58:59], v[58:59], v[8:9]
	global_store_dwordx4 v1, v[56:59], s[26:27]
	s_add_u32 s26, s26, 0x200000
	s_addc_u32 s27, s27, 0
	s_waitcnt vmcnt(15)
	v_pk_mul_f32 v[60:61], v[60:61], v[20:21] op_sel_hi:[1,0]
	v_pk_mul_f32 v[62:63], v[62:63], v[20:21] op_sel_hi:[1,0]
	v_pk_mul_f32 v[60:61], v[60:61], v[6:7]
	v_pk_mul_f32 v[62:63], v[62:63], v[8:9]
	global_store_dwordx4 v1, v[60:63], s[26:27]
	s_add_u32 s26, s26, 0x200000
	s_addc_u32 s27, s27, 0
	s_waitcnt vmcnt(15)
; __device__ __forceinline__ void ph_final_norm(float* H, const float* __restrict__ rowss, const float* __restrict__ g, size_t gt, size_t NGT) {
;     const size_t n4 = (size_t)SEQ * DM / 4;
;     f32x4* h4 = (f32x4*)H;
;     for (size_t i0 = gt; i0 < n4; i0 += 8 * NGT) {
;         f32x4 v[8]; float rs[8];
; #pragma unroll
;         for (int k = 0; k < 8; ++k) { const size_t i = i0 + k * NGT; v[k] = h4[i]; rs[k] = rowss[i >> 10]; }
; #pragma unroll
;         for (int k = 0; k < 8; ++k) { const size_t i = i0 + k * NGT; const f32x4 gg = ((const f32x4*)g)[i & 1023]; h4[i] = v[k] * rsqrtf(rs[k] * (1.f / DM) + EPS) * gg; }
;     }
	v_pk_mul_f32 v[64:65], v[64:65], v[22:23] op_sel_hi:[1,0]
	v_pk_mul_f32 v[66:67], v[66:67], v[22:23] op_sel_hi:[1,0]
	v_pk_mul_f32 v[64:65], v[64:65], v[6:7]
	v_pk_mul_f32 v[66:67], v[66:67], v[8:9]
	global_store_dwordx4 v1, v[64:67], s[26:27]
	s_add_u32 s26, s26, 0x200000
	s_addc_u32 s27, s27, 0
	s_waitcnt vmcnt(15)
	v_pk_mul_f32 v[68:69], v[68:69], v[24:25] op_sel_hi:[1,0]
	v_pk_mul_f32 v[70:71], v[70:71], v[24:25] op_sel_hi:[1,0]
	v_pk_mul_f32 v[68:69], v[68:69], v[6:7]
	v_pk_mul_f32 v[70:71], v[70:71], v[8:9]
	global_store_dwordx4 v1, v[68:71], s[26:27]
	s_add_u32 s26, s26, 0x200000
	s_addc_u32 s27, s27, 0
	s_waitcnt vmcnt(15)
	v_pk_mul_f32 v[72:73], v[72:73], v[26:27] op_sel_hi:[1,0]
	v_pk_mul_f32 v[74:75], v[74:75], v[26:27] op_sel_hi:[1,0]
	v_pk_mul_f32 v[72:73], v[72:73], v[6:7]
	v_pk_mul_f32 v[74:75], v[74:75], v[8:9]
	global_store_dwordx4 v1, v[72:75], s[26:27]
	s_add_u32 s26, s26, 0x200000
	s_addc_u32 s27, s27, 0
	s_waitcnt vmcnt(15)
	v_pk_mul_f32 v[76:77], v[76:77], v[28:29] op_sel_hi:[1,0]
	v_pk_mul_f32 v[78:79], v[78:79], v[28:29] op_sel_hi:[1,0]
	v_pk_mul_f32 v[76:77], v[76:77], v[6:7]
	v_pk_mul_f32 v[78:79], v[78:79], v[8:9]
	global_store_dwordx4 v1, v[76:79], s[26:27]
	s_add_u32 s26, s26, 0x200000
	s_addc_u32 s27, s27, 0
	s_waitcnt vmcnt(15)
	v_pk_mul_f32 v[80:81], v[80:81], v[30:31] op_sel_hi:[1,0]
	v_pk_mul_f32 v[82:83], v[82:83], v[30:31] op_sel_hi:[1,0]
	v_pk_mul_f32 v[80:81], v[80:81], v[6:7]
	v_pk_mul_f32 v[82:83], v[82:83], v[8:9]
	global_store_dwordx4 v1, v[80:83], s[26:27]
	s_add_u32 s26, s26, 0x200000
	s_addc_u32 s27, s27, 0
	s_waitcnt vmcnt(15)
	v_pk_mul_f32 v[84:85], v[84:85], v[32:33] op_sel_hi:[1,0]
	v_pk_mul_f32 v[86:87], v[86:87], v[32:33] op_sel_hi:[1,0]
	v_pk_mul_f32 v[84:85], v[84:85], v[6:7]
	v_pk_mul_f32 v[86:87], v[86:87], v[8:9]
	global_store_dwordx4 v1, v[84:87], s[26:27]
	s_add_u32 s26, s26, 0x200000
	s_addc_u32 s27, s27, 0
	s_waitcnt vmcnt(15)
	v_pk_mul_f32 v[88:89], v[88:89], v[34:35] op_sel_hi:[1,0]
	v_pk_mul_f32 v[90:91], v[90:91], v[34:35] op_sel_hi:[1,0]
	v_pk_mul_f32 v[88:89], v[88:89], v[6:7]
	v_pk_mul_f32 v[90:91], v[90:91], v[8:9]
	global_store_dwordx4 v1, v[88:91], s[26:27]
	s_add_u32 s26, s26, 0x200000
	s_addc_u32 s27, s27, 0
	s_waitcnt vmcnt(15)
	v_pk_mul_f32 v[92:93], v[92:93], v[36:37] op_sel_hi:[1,0]
	v_pk_mul_f32 v[94:95], v[94:95], v[36:37] op_sel_hi:[1,0]
	v_pk_mul_f32 v[92:93], v[92:93], v[6:7]
	v_pk_mul_f32 v[94:95], v[94:95], v[8:9]
	global_store_dwordx4 v1, v[92:95], s[26:27]
	s_add_u32 s26, s26, 0x200000
	s_addc_u32 s27, s27, 0
	s_waitcnt vmcnt(15)
	v_pk_mul_f32 v[96:97], v[96:97], v[38:39] op_sel_hi:[1,0]
	v_pk_mul_f32 v[98:99], v[98:99], v[38:39] op_sel_hi:[1,0]
	v_pk_mul_f32 v[96:97], v[96:97], v[6:7]
	v_pk_mul_f32 v[98:99], v[98:99], v[8:9]
	global_store_dwordx4 v1, v[96:99], s[26:27]
	s_add_u32 s26, s26, 0x200000
	s_addc_u32 s27, s27, 0
	s_waitcnt vmcnt(15)
	v_pk_mul_f32 v[100:101], v[100:101], v[40:41] op_sel_hi:[1,0]
	v_pk_mul_f32 v[102:103], v[102:103], v[40:41] op_sel_hi:[1,0]
	v_pk_mul_f32 v[100:101], v[100:101], v[6:7]
	v_pk_mul_f32 v[102:103], v[102:103], v[8:9]
	global_store_dwordx4 v1, v[100:103], s[26:27]
	s_add_u32 s26, s26, 0x200000
	s_addc_u32 s27, s27, 0
	s_waitcnt vmcnt(15)
	v_pk_mul_f32 v[104:105], v[104:105], v[42:43] op_sel_hi:[1,0]
	v_pk_mul_f32 v[106:107], v[106:107], v[42:43] op_sel_hi:[1,0]
	v_pk_mul_f32 v[104:105], v[104:105], v[6:7]
	v_pk_mul_f32 v[106:107], v[106:107], v[8:9]
	global_store_dwordx4 v1, v[104:107], s[26:27]
	s_add_u32 s24, s24, 0x2000000
	s_addc_u32 s25, s25, 0
	s_add_u32 s20, s20, 0x2000
	s_addc_u32 s21, s21, 0
	s_add_i32 s22, s22, 1
	s_cmp_lt_u32 s22, 8
	s_cbranch_scc1 .Lp9_loop
	s_branch .LBB0_1538
.Lp9_orig:
	s_ashr_i32 s3, s2, 31
	s_lshl_b64 s[0:1], s[2:3], 9
	v_ashrrev_i32_e32 v1, 31, v0
	v_lshl_add_u64 v[30:31], s[0:1], 0, v[0:1]
	s_mov_b64 s[0:1], 0x1000000
	v_cmp_gt_u64_e32 vcc, s[0:1], v[30:31]
	s_and_saveexec_b64 s[0:1], vcc
	s_cbranch_execz .LBB0_1538
	s_load_dwordx2 s[0:1], s[92:93], 0xb8
	s_waitcnt lgkmcnt(0)
	s_load_dwordx4 s[16:19], s[92:93], 0xa8
	s_ashr_i32 s75, s74, 31
	s_lshl_b64 s[14:15], s[74:75], 9
	s_mul_hi_i32 s23, s74, 0xe000
	s_add_u32 s20, s0, 0x60000
	s_addc_u32 s21, s1, 0
	s_lshl_b32 s0, s2, 9
	s_add_i32 s1, s74, s2
	s_lshl_b32 s1, s1, 9
	v_add_u16_e32 v3, s0, v0
	v_add_u16_e32 v2, s1, v0
	v_and_b32_e32 v3, 0x3ff, v3
	v_lshlrev_b32_e32 v10, 4, v3
	v_and_b32_e32 v2, 0x3ff, v2
	v_lshlrev_b32_e32 v11, 4, v2
	s_waitcnt lgkmcnt(0)
	global_load_dwordx4 v[2:5], v10, s[16:17]
	global_load_dwordx4 v[6:9], v11, s[16:17]
	s_lshl_b64 s[0:1], s[2:3], 13
	s_add_u32 s0, s18, s0
	s_addc_u32 s1, s19, s1
	s_mul_i32 s22, s74, 0xe000
	v_lshl_add_u64 v[0:1], v[0:1], 4, s[0:1]
	s_lshl_b64 s[18:19], s[74:75], 16
	s_mul_hi_i32 s25, s74, 0xc000
	s_mul_i32 s24, s74, 0xc000
	s_mul_hi_i32 s27, s74, 0xa000
	s_mul_i32 s26, s74, 0xa000
	s_lshl_b64 s[28:29], s[74:75], 15
	s_mul_hi_i32 s31, s74, 0x6000
	s_mul_i32 s30, s74, 0x6000
	s_lshl_b64 s[34:35], s[74:75], 14
	s_lshl_b64 s[36:37], s[74:75], 13
	s_lshl_b64 s[38:39], s[74:75], 10
	s_mul_hi_i32 s41, s74, 0x600
	s_mul_i32 s40, s74, 0x600
	s_lshl_b64 s[42:43], s[74:75], 11
	s_mul_hi_i32 s45, s74, 0xa00
	s_mul_i32 s44, s74, 0xa00
	s_mul_hi_i32 s47, s74, 0xc00
	s_mul_i32 s46, s74, 0xc00
	s_mul_hi_i32 s49, s74, 0xe00
	s_mul_i32 s48, s74, 0xe00
	s_mov_b64 s[50:51], 0
	v_mov_b32_e32 v32, 0x358637bd
	s_mov_b32 s33, 0x800000
	s_mov_b64 s[52:53], 0xffffff
